# phase 4: blocks >= 256 walk their items in reverse (conv tiles first) so co-resident blocks run complementary tile types
# baseline (speedup 1.0000x reference)
; DEV void phase_qkv_conv(const Params& p, char* smem) {
;   EpiQ eq{WSP(bf16_t, R_Q), WSP(bf16_t, R_QC), WSP(float, S_ROPEC), WSP(float, S_ROPES)};
;   EpiKV ekv{WSP(bf16_t, R_K), WSP(bf16_t, R_VT)};
;   for (int item = blockIdx.x; item < NI_GQ + NI_GKV + NI_CONV; item += gridDim.x) {
;     int it = item;
.LBB0_772:
	s_andn2_b64 vcc, exec, s[0:1]
	s_cbranch_vccnz .LBB0_1137
	s_cmp_lt_i32 s57, 2
	s_mov_b64 s[0:1], -1
	s_cbranch_scc1 .LBB0_1052
	s_cmp_lt_i32 s57, 3
	s_cbranch_scc1 .LBB0_1033
	s_cmp_gt_i32 s57, 3
	s_cbranch_scc0 .LBB0_1021
	v_readlane_b32 s0, v252, 56
	v_readlane_b32 s1, v252, 57
	s_andn2_b64 vcc, exec, s[0:1]
	s_cbranch_vccnz .LBB0_1020
	v_readlane_b32 s6, v254, 0
	v_readlane_b32 s7, v254, 1
	s_add_u32 s0, s6, 0xbf80000
	s_addc_u32 s1, s7, 0
	s_add_u32 s2, s6, 0xc000000
	s_addc_u32 s3, s7, 0
	s_add_u32 s8, s6, 0x16d00000
	s_addc_u32 s9, s7, 0
	s_add_u32 s18, s6, 0x18600000
	v_writelane_b32 v254, s8, 6
	s_addc_u32 s19, s7, 0
	s_mov_b32 s16, s51
	s_cmp_eq_u32 s86, 0x200
	s_cbranch_scc0 .Lp4_fwd
	s_cmp_lt_u32 s51, 0x100
	s_cbranch_scc1 .Lp4_fwd
	s_sub_i32 s16, 0xf77, s51
	s_lshr_b32 s16, s16, 9
	s_lshl_b32 s16, s16, 9
	s_add_i32 s16, s16, s51
.Lp4_fwd:
	v_writelane_b32 v254, s9, 7
	s_add_u32 s8, s6, 0x14300000
	s_addc_u32 s9, s7, 0
	s_add_u32 s48, s6, 0x13e00000
	s_addc_u32 s49, s7, 0
	s_add_u32 s14, s6, 0xa6a0000
	s_addc_u32 s15, s7, 0
	s_add_u32 s28, s6, 0x13500000
	v_writelane_b32 v254, s8, 8
	s_addc_u32 s29, s7, 0
	s_nop 0
	v_writelane_b32 v254, s9, 9
	s_add_u32 s8, s6, 0xa640000
	s_addc_u32 s9, s7, 0
	s_branch .LBB0_781

; DEV void phase_qkv_conv(const Params& p, char* smem) {
;     ...
;   for (int item = blockIdx.x; item < NI_GQ + NI_GKV + NI_CONV; item += gridDim.x) {
.LBB0_780:
	s_cmp_eq_u32 s86, 0x200
	s_cbranch_scc0 .Lp4_inc
	s_cmp_lt_u32 s51, 0x100
	s_cbranch_scc1 .Lp4_inc
	s_sub_i32 s16, s16, s86
	s_branch .Lp4_chk

; DEV void phase_qkv_conv(const Params& p, char* smem) {
;     ...
;   for (int item = blockIdx.x; item < NI_GQ + NI_GKV + NI_CONV; item += gridDim.x) {
.Lp4_chk:
	s_cmpk_gt_u32 s16, 0xf77
	s_cbranch_scc1 .LBB0_1020
